# v31 + chunk-MLP: the barrier at each task start no longer waits for the previous task's output stores (vmcnt(0) dropped; the barrier only guards LDS reuse)
# speedup vs baseline: 1.0037x; 1.0037x over previous
.LBB0_350:
	s_ashr_i32 s4, s60, 9
	s_ashr_i32 s5, s4, 31
	s_lshl_b64 s[50:51], s[4:5], 13
	s_and_b32 s4, s59, 0x1f80
	s_or_b32 s50, s50, s4
	s_nop 0
	s_barrier
	s_and_saveexec_b64 s[52:53], s[6:7]
	s_cbranch_execz .LBB0_352
	v_mov_b32_e32 v1, s51
	v_or_b32_e32 v0, s50, v196
	v_lshlrev_b64 v[0:1], 6, v[0:1]
	v_lshl_add_u64 v[16:17], s[48:49], 0, v[0:1]
	flat_load_dwordx4 v[0:3], v[16:17]
	flat_load_dwordx4 v[4:7], v[16:17] offset:16
	flat_load_dwordx4 v[8:11], v[16:17] offset:32
	s_nop 0
	flat_load_dwordx4 v[16:19], v[16:17] offset:48
	s_waitcnt vmcnt(0) lgkmcnt(0)
	v_pk_add_f32 v[0:1], v[0:1], v[4:5]
	v_pk_add_f32 v[2:3], v[2:3], v[6:7]
	v_pk_add_f32 v[0:1], v[0:1], v[8:9]
	v_pk_add_f32 v[2:3], v[2:3], v[10:11]
	v_pk_add_f32 v[0:1], v[0:1], v[16:17]
	v_pk_add_f32 v[2:3], v[2:3], v[18:19]
	v_add_f32_e32 v0, v0, v1
	v_add_f32_e32 v0, v2, v0
	v_add_f32_e32 v0, v3, v0
	v_fmamk_f32 v0, v0, 0x3a800000, v105
	v_mul_f32_e32 v1, 0x4b800000, v0
	v_cmp_gt_f32_e32 vcc, s56, v0
	s_nop 1
	v_cndmask_b32_e32 v0, v0, v1, vcc
	v_rsq_f32_e32 v0, v0
	s_nop 0
	v_mul_f32_e32 v1, 0x45800000, v0
	v_cndmask_b32_e32 v0, v0, v1, vcc
	ds_write_b32 v21, v0
